# ret_kv KV f32 stores write-through (sc1) too
# baseline (speedup 1.0000x reference)
; #define LAS __attribute__((address_space(3)))
; __device__ __forceinline__ unsigned pk2(float lo, float hi) { return pg8::cvt_pk_bf16(lo, hi); }
; __device__ __forceinline__ float ret_lg2(int h) { return log2f(1.0f - exp2f(-5.0f - (float)h)); }
; template <int NR, bool ZETA> __device__ __forceinline__ void ret_load_R(const bf16* Z, int r0, int c0, LAS unsigned char* dst, int tid, float lg2) {
; #pragma unroll
;     for (int it = 0; it < NR / 32; ++it) { const int ch = it * NTHR + tid, r = ch >> 4, c = ch & 15;
;         u32x4 v = *(const u32x4*)(Z + (size_t)(r0 + r) * IW + c0 + c * 8);
;         if (ZETA) { const float zs = __builtin_amdgcn_exp2f((float)(127 - r) * lg2); float f[8]; unpack8(v, f);
;             v.x = pk2(f[0] * zs, f[1] * zs); v.y = pk2(f[2] * zs, f[3] * zs); v.z = pk2(f[4] * zs, f[5] * zs); v.w = pk2(f[6] * zs, f[7] * zs); }
;         *(LAS u32x4*)(dst + (r * 136 + c * 8) * 2) = v; }
; }
; __device__ __forceinline__ void ret_kv(const Args& a, int unit, LAS unsigned char* lds, int tid, int lane, int wave) {
;     const bf16* Z = (const bf16*)(a.ws + WS_HZ);
;     const int n = unit & 63, bh = unit >> 6, h = bh & 3, b = bh >> 2, r0 = b * SEQ + n * 128, fr = lane & 15, fq = lane >> 4;
;     const float lg2 = ret_lg2(h);
;     ret_load_R<128, true>(Z, r0, 768 + h * 128, lds + OFF_KS, tid, lg2);
;     ret_load_R<128, false>(Z, r0, 1280 + h * 128, lds + OFF_VT, tid, lg2);
;     __syncthreads();
.LBB0_1263:
	s_bfe_u32 s1, s4, 0x20006
	v_cvt_f32_ubyte0_e32 v0, s1
	v_sub_f32_e32 v0, 0xc0a00000, v0
	v_cmp_gt_f32_e32 vcc, s87, v0
	s_lshl_b32 s0, s4, 5
	s_lshl_b32 s5, s4, 7
	v_cndmask_b32_e32 v1, 0, v192, vcc
	v_add_f32_e32 v0, v0, v1
	s_and_b32 s0, s0, 0xffffe000
	s_and_b32 s5, s5, 0x1f80
	v_exp_f32_e32 v0, v0
	s_or_b32 s0, s0, s5
	s_and_b64 s[28:29], vcc, exec
	s_cselect_b32 s5, 0xffffffc0, 0
	v_ldexp_f32 v0, v0, s5
	v_sub_f32_e32 v1, 1.0, v0
	v_cmp_gt_f32_e32 vcc, s33, v1
	s_and_b64 s[28:29], vcc, exec
	s_cselect_b32 s5, 32, 0
	s_lshl_b32 s1, s1, 8
	v_lshlrev_b32_e32 v0, 3, v76
	s_add_u32 s28, s8, s1
	v_and_b32_e32 v0, 0x78, v0
	s_addc_u32 s29, s9, 0
	v_lshlrev_b32_e32 v144, 1, v0
	v_ashrrev_i32_e32 v16, 4, v76
	v_lshl_add_u64 v[10:11], s[28:29], 0, v[144:145]
	v_add_u32_e32 v2, s0, v16
	v_mad_i64_i32 v[12:13], s[28:29], v2, s84, v[10:11]
	global_load_dwordx4 v[2:5], v[12:13], off offset:1536
	v_ldexp_f32 v1, v1, s5
	v_add_u32_e32 v7, 0x200, v76
	v_sub_u32_e32 v8, 0x7f, v16
	v_log_f32_e32 v1, v1
	v_ashrrev_i32_e32 v18, 4, v7
	v_cvt_f32_i32_e32 v7, v8
	v_cndmask_b32_e32 v6, 0, v193, vcc
	v_sub_f32_e32 v1, v1, v6
	v_add_u32_e32 v8, s0, v18
	v_mul_f32_e32 v6, v1, v7
	v_exp_f32_e32 v6, v6
	v_mad_i64_i32 v[14:15], s[28:29], v8, s84, v[10:11]
	global_load_dwordx4 v[118:121], v[14:15], off offset:1536
	s_movk_i32 s5, 0x88
	v_lshrrev_b32_e32 v26, 2, v66
	v_lshlrev_b32_e32 v28, 3, v66
	s_movk_i32 s16, 0x110
	v_lshlrev_b32_e32 v27, 2, v66
	v_and_b32_e32 v28, 24, v28
	v_and_b32_e32 v144, 48, v66
	s_waitcnt vmcnt(1)
	v_lshlrev_b32_e32 v7, 16, v2
	v_and_b32_e32 v2, 0xffff0000, v2
	v_lshlrev_b32_e32 v8, 16, v3
	v_and_b32_e32 v3, 0xffff0000, v3
	v_lshlrev_b32_e32 v9, 16, v4
	v_and_b32_e32 v4, 0xffff0000, v4
	v_lshlrev_b32_e32 v17, 16, v5
	v_and_b32_e32 v5, 0xffff0000, v5
	v_mul_f32_e32 v7, v6, v7
	v_mul_f32_e32 v2, v6, v2
	v_mul_f32_e32 v8, v6, v8
	v_mul_f32_e32 v3, v6, v3
	v_mul_f32_e32 v9, v6, v9
	v_mul_f32_e32 v4, v6, v4
	v_mul_f32_e32 v5, v6, v5
	v_mul_f32_e32 v17, v6, v17
	v_cvt_pk_bf16_f32 v2, v7, v2
	v_cvt_pk_bf16_f32 v3, v8, v3
	v_cvt_pk_bf16_f32 v4, v9, v4
	v_cvt_pk_bf16_f32 v5, v17, v5
	v_add_u32_e32 v17, 0x400, v76
	v_ashrrev_i32_e32 v20, 4, v17
	v_mad_u64_u32 v[16:17], s[28:29], v16, s5, v[0:1]
	v_sub_u32_e32 v17, 0x7f, v18
	v_cvt_f32_i32_e32 v19, v17
	v_lshl_add_u32 v22, v16, 1, 0
	v_add_u32_e32 v16, s0, v20
	ds_write_b128 v22, v[2:5] offset:17408
	v_mul_f32_e32 v19, v1, v19
	v_exp_f32_e32 v19, v19
	v_mad_i64_i32 v[16:17], s[28:29], v16, s84, v[10:11]
	global_load_dwordx4 v[122:125], v[16:17], off offset:1536
	s_waitcnt vmcnt(1)
	v_lshlrev_b32_e32 v2, 16, v118
	v_and_b32_e32 v3, 0xffff0000, v118
	v_lshlrev_b32_e32 v4, 16, v119
	v_and_b32_e32 v5, 0xffff0000, v119
	v_lshlrev_b32_e32 v6, 16, v120
	v_and_b32_e32 v7, 0xffff0000, v120
	v_lshlrev_b32_e32 v8, 16, v121
	v_and_b32_e32 v9, 0xffff0000, v121
	v_mul_f32_e32 v2, v19, v2
	v_mul_f32_e32 v3, v19, v3
	v_mul_f32_e32 v4, v19, v4
	v_mul_f32_e32 v5, v19, v5
	v_mul_f32_e32 v6, v19, v6
	v_mul_f32_e32 v7, v19, v7
	v_mul_f32_e32 v8, v19, v8
	v_mul_f32_e32 v9, v19, v9
	v_cvt_pk_bf16_f32 v2, v2, v3
	v_cvt_pk_bf16_f32 v3, v4, v5
	v_cvt_pk_bf16_f32 v4, v6, v7
	v_cvt_pk_bf16_f32 v5, v8, v9
	v_add_u32_e32 v19, 0x600, v76
	v_ashrrev_i32_e32 v23, 4, v19
	v_mad_u64_u32 v[18:19], s[28:29], v18, s5, v[0:1]
	v_sub_u32_e32 v19, 0x7f, v20
	v_cvt_f32_i32_e32 v21, v19
	v_lshl_add_u32 v24, v18, 1, 0
	v_add_u32_e32 v18, s0, v23
	v_mad_i64_i32 v[18:19], s[0:1], v18, s84, v[10:11]
	global_load_dwordx4 v[118:121], v[18:19], off offset:1536
	v_mul_f32_e32 v10, v1, v21
	v_exp_f32_e32 v10, v10
	ds_write_b128 v24, v[2:5] offset:17408
	s_waitcnt vmcnt(1)
	v_lshlrev_b32_e32 v2, 16, v122
	v_and_b32_e32 v3, 0xffff0000, v122
	v_lshlrev_b32_e32 v4, 16, v123
	v_and_b32_e32 v5, 0xffff0000, v123
	v_lshlrev_b32_e32 v6, 16, v124
	v_and_b32_e32 v7, 0xffff0000, v124
	v_lshlrev_b32_e32 v8, 16, v125
	v_and_b32_e32 v9, 0xffff0000, v125
	v_mul_f32_e32 v2, v10, v2
	v_mul_f32_e32 v3, v10, v3
	v_mul_f32_e32 v4, v10, v4
	v_mul_f32_e32 v5, v10, v5
	v_mul_f32_e32 v6, v10, v6
	v_mul_f32_e32 v7, v10, v7
	v_mul_f32_e32 v8, v10, v8
	v_mul_f32_e32 v9, v10, v9
	v_cvt_pk_bf16_f32 v2, v2, v3
	v_cvt_pk_bf16_f32 v3, v4, v5
	v_cvt_pk_bf16_f32 v4, v6, v7
	v_cvt_pk_bf16_f32 v5, v8, v9
	v_sub_u32_e32 v10, 0x7f, v23
	v_cvt_f32_i32_e32 v21, v10
	v_mad_u64_u32 v[10:11], s[0:1], v20, s5, v[0:1]
	v_lshl_add_u32 v25, v10, 1, 0
	v_mul_f32_e32 v1, v1, v21
	global_load_dwordx4 v[18:21], v[18:19], off offset:2560
	v_exp_f32_e32 v1, v1
	ds_write_b128 v25, v[2:5] offset:17408
	s_waitcnt vmcnt(1)
	v_lshlrev_b32_e32 v2, 16, v118
	v_and_b32_e32 v3, 0xffff0000, v118
	v_lshlrev_b32_e32 v4, 16, v119
	v_and_b32_e32 v5, 0xffff0000, v119
	v_lshlrev_b32_e32 v6, 16, v120
	v_and_b32_e32 v7, 0xffff0000, v120
	v_lshlrev_b32_e32 v8, 16, v121
	v_and_b32_e32 v9, 0xffff0000, v121
	v_mul_f32_e32 v2, v1, v2
	v_mul_f32_e32 v3, v1, v3
	v_mul_f32_e32 v4, v1, v4
	v_mul_f32_e32 v5, v1, v5
	v_mul_f32_e32 v6, v1, v6
	v_mul_f32_e32 v7, v1, v7
	v_mul_f32_e32 v8, v1, v8
	v_mul_f32_e32 v1, v1, v9
	v_cvt_pk_bf16_f32 v2, v2, v3
	v_cvt_pk_bf16_f32 v3, v4, v5
	v_cvt_pk_bf16_f32 v4, v6, v7
	v_cvt_pk_bf16_f32 v5, v8, v1
	global_load_dwordx4 v[6:9], v[12:13], off offset:2560
	global_load_dwordx4 v[10:13], v[14:15], off offset:2560
	s_nop 0
	global_load_dwordx4 v[14:17], v[16:17], off offset:2560
	s_nop 0
	s_nop 0
	v_lshrrev_b32_e32 v1, 1, v76
	v_and_b32_e32 v29, 24, v1
	v_mad_u64_u32 v[0:1], s[0:1], v23, s5, v[0:1]
	v_and_or_b32 v56, v26, 3, v29
	s_lshl_b32 s1, s26, 5
	v_mad_u32_u24 v1, v56, s16, 0
	s_and_b32 s0, s1, 0x60
	v_add_u32_e32 v26, v1, v28
	s_and_b32 s5, s1, 0xffffff80
	s_or_b32 s1, s1, 0x60
	v_and_or_b32 v23, v27, 12, s0
	v_lshl_add_u32 v0, v0, 1, 0
	v_add_u32_e32 v57, s5, v26
	v_lshlrev_b32_e32 v58, 1, v23
	v_add_u32_e32 v59, s1, v26
	v_add_u32_e32 v48, v1, v58
	ds_write_b128 v0, v[2:5] offset:17408
	s_waitcnt vmcnt(2)
	ds_write_b128 v22, v[6:9] offset:52224
	s_waitcnt vmcnt(1)
	ds_write_b128 v24, v[10:13] offset:52224
	s_waitcnt vmcnt(0)
	ds_write_b128 v25, v[14:17] offset:52224
	s_waitcnt vmcnt(0)
	ds_write_b128 v0, v[18:21] offset:52224
	s_waitcnt lgkmcnt(0)
	s_barrier
; #define MFMA16(X, Y, ACC) ACC = __builtin_amdgcn_mfma_f32_16x16x32_bf16(X, Y, ACC, 0, 0, 0)
; __device__ __forceinline__ void ret_kv(const Args& a, int unit, LAS unsigned char* lds, int tid, int lane, int wave) {
;     ...
;     const int eb = (wave & 3) * 32, dh = (wave >> 2) * 64;
;     f32x4 acc[2][4];
; #pragma unroll
;     for (int i = 0; i < 2; ++i)
; #pragma unroll
;         for (int j = 0; j < 4; ++j) acc[i][j] = (f32x4){0.f, 0.f, 0.f, 0.f};
; #pragma unroll
;     for (int ks = 0; ks < 4; ++ks) {
;         bf16x8 vf[2], kf[4];
; #pragma unroll
;         for (int i = 0; i < 2; ++i) vf[i] = tr_frag(lds + OFF_VT, 272, 32 * ks, eb + i * 16, lane);
; #pragma unroll
;         for (int j = 0; j < 4; ++j) kf[j] = tr_frag(lds + OFF_KS, 272, 32 * ks, dh + j * 16, lane);
; #pragma unroll
;         for (int i = 0; i < 2; ++i)
; #pragma unroll
;             for (int j = 0; j < 4; ++j) MFMA16(kf[j], vf[i], acc[i][j]);
;         asm volatile("" ::: "memory");
;     }
;     float* KV = (float*)(a.ws + WS_KV) + (size_t)unit * 16384;
; #pragma unroll
;     for (int i = 0; i < 2; ++i)
; #pragma unroll
;         for (int j = 0; j < 4; ++j) *(f32x4*)(KV + (size_t)(eb + i * 16 + fr) * 128 + dh + j * 16 + 4 * fq) = acc[i][j];
;     __syncthreads();
	ds_read_b64_tr_b16 v[2:3], v57 offset:18496
	ds_read_b64_tr_b16 v[0:1], v57 offset:17408
	ds_read_b64_tr_b16 v[4:5], v57 offset:17440
	ds_read_b64_tr_b16 v[6:7], v57 offset:18528
	ds_read_b64_tr_b16 v[10:11], v48 offset:53312
	ds_read_b64_tr_b16 v[8:9], v48 offset:52224
	ds_read_b64_tr_b16 v[14:15], v48 offset:53344
	ds_read_b64_tr_b16 v[12:13], v48 offset:52256
	ds_read_b64_tr_b16 v[16:17], v57 offset:17472
	ds_read_b64_tr_b16 v[18:19], v57 offset:18560
	ds_read_b64_tr_b16 v[24:25], v59 offset:17408
	ds_read_b64_tr_b16 v[26:27], v59 offset:18496
	s_waitcnt lgkmcnt(6)
	v_mfma_f32_16x16x32_bf16 v[20:23], v[0:3], v[8:11], 0
	ds_read_b64_tr_b16 v[38:39], v57 offset:27200
	ds_read_b64_tr_b16 v[36:37], v57 offset:26112
	ds_read_b64_tr_b16 v[42:43], v48 offset:62016
	ds_read_b64_tr_b16 v[40:41], v48 offset:60928
	ds_read_b64_tr_b16 v[44:45], v57 offset:26144
	ds_read_b64_tr_b16 v[46:47], v57 offset:27232
	v_add_u32_e32 v60, s18, v58
	v_mfma_f32_16x16x32_bf16 v[28:31], v[4:7], v[8:11], 0
	s_lshl_b32 s1, s26, 4
	s_ashr_i32 s5, s4, 31
	s_and_b32 s28, s1, 0xffffffc0
	s_waitcnt lgkmcnt(8)
	v_mfma_f32_16x16x32_bf16 v[32:35], v[16:19], v[8:11], 0
	s_lshl_b64 s[4:5], s[4:5], 16
	s_waitcnt lgkmcnt(6)
	v_mfma_f32_16x16x32_bf16 v[8:11], v[24:27], v[8:11], 0
	v_mfma_f32_16x16x32_bf16 v[0:3], v[0:3], v[12:15], 0
	v_mfma_f32_16x16x32_bf16 v[4:7], v[4:7], v[12:15], 0
	v_mfma_f32_16x16x32_bf16 v[16:19], v[16:19], v[12:15], 0
	v_mfma_f32_16x16x32_bf16 v[12:15], v[24:27], v[12:15], 0
	ds_read_b64_tr_b16 v[26:27], v48 offset:62048
	ds_read_b64_tr_b16 v[24:25], v48 offset:60960
	ds_read_b64_tr_b16 v[48:49], v57 offset:26176
	ds_read_b64_tr_b16 v[50:51], v57 offset:27264
	ds_read_b64_tr_b16 v[52:53], v59 offset:26112
	ds_read_b64_tr_b16 v[54:55], v59 offset:27200
	s_waitcnt lgkmcnt(8)
	v_mfma_f32_16x16x32_bf16 v[20:23], v[36:39], v[40:43], v[20:23]
	s_waitcnt lgkmcnt(6)
	v_mfma_f32_16x16x32_bf16 v[28:31], v[44:47], v[40:43], v[28:31]
	s_waitcnt lgkmcnt(2)
	v_mfma_f32_16x16x32_bf16 v[32:35], v[48:51], v[40:43], v[32:35]
	s_waitcnt lgkmcnt(0)
	v_mfma_f32_16x16x32_bf16 v[8:11], v[52:55], v[40:43], v[8:11]
	v_mov_b32_e32 v40, 0x4400
	v_mad_u32_u24 v40, v56, s16, v40
	v_add3_u32 v61, s18, v40, v58
	v_mfma_f32_16x16x32_bf16 v[0:3], v[36:39], v[24:27], v[0:3]
	v_add_u32_e32 v42, v60, v40
	ds_read_b64_tr_b16 v[38:39], v57 offset:35904
	ds_read_b64_tr_b16 v[36:37], v57 offset:34816
	v_mfma_f32_16x16x32_bf16 v[4:7], v[44:47], v[24:27], v[4:7]
	ds_read_b64_tr_b16 v[40:41], v42
	ds_read_b64_tr_b16 v[42:43], v42 offset:1088
	ds_read_b64_tr_b16 v[44:45], v57 offset:34848
	ds_read_b64_tr_b16 v[46:47], v57 offset:35936
	v_mfma_f32_16x16x32_bf16 v[16:19], v[48:51], v[24:27], v[16:19]
	v_mfma_f32_16x16x32_bf16 v[12:15], v[52:55], v[24:27], v[12:15]
	ds_read_b64_tr_b16 v[24:25], v61 offset:32
	ds_read_b64_tr_b16 v[26:27], v61 offset:1120
	ds_read_b64_tr_b16 v[48:49], v57 offset:34880
	ds_read_b64_tr_b16 v[50:51], v57 offset:35968
	ds_read_b64_tr_b16 v[52:53], v59 offset:34816
	ds_read_b64_tr_b16 v[54:55], v59 offset:35904
	s_waitcnt lgkmcnt(8)
	v_mfma_f32_16x16x32_bf16 v[20:23], v[36:39], v[40:43], v[20:23]
	s_waitcnt lgkmcnt(4)
	v_mfma_f32_16x16x32_bf16 v[0:3], v[36:39], v[24:27], v[0:3]
	v_mov_b32_e32 v36, 0x6600
	v_mad_u32_u24 v36, v56, s16, v36
	v_readlane_b32 s16, v252, 48
	v_mfma_f32_16x16x32_bf16 v[28:31], v[44:47], v[40:43], v[28:31]
	v_readlane_b32 s17, v252, 49
	s_add_u32 s4, s16, s4
	s_addc_u32 s5, s17, s5
	v_mfma_f32_16x16x32_bf16 v[4:7], v[44:47], v[24:27], v[4:7]
	v_add3_u32 v46, s18, v36, v58
	v_add_u32_e32 v44, v60, v36
	s_ashr_i32 s29, s28, 31
	s_waitcnt lgkmcnt(2)
	v_mfma_f32_16x16x32_bf16 v[32:35], v[48:51], v[40:43], v[32:35]
	v_and_or_b32 v56, v76, 15, s0
	s_lshl_b64 s[0:1], s[28:29], 2
	s_add_u32 s0, s4, s0
	s_waitcnt lgkmcnt(0)
	v_mfma_f32_16x16x32_bf16 v[8:11], v[52:55], v[40:43], v[8:11]
	ds_read_b64_tr_b16 v[38:39], v57 offset:44608
	ds_read_b64_tr_b16 v[36:37], v57 offset:43520
	ds_read_b64_tr_b16 v[40:41], v57 offset:43552
	ds_read_b64_tr_b16 v[42:43], v57 offset:44640
	s_addc_u32 s1, s5, s1
	v_mfma_f32_16x16x32_bf16 v[16:19], v[48:51], v[24:27], v[16:19]
	v_mfma_f32_16x16x32_bf16 v[12:15], v[52:55], v[24:27], v[12:15]
	ds_read_b64_tr_b16 v[24:25], v44
	ds_read_b64_tr_b16 v[26:27], v44 offset:1088
	ds_read_b64_tr_b16 v[44:45], v46 offset:32
	ds_read_b64_tr_b16 v[46:47], v46 offset:1120
	ds_read_b64_tr_b16 v[48:49], v57 offset:43584
	ds_read_b64_tr_b16 v[50:51], v57 offset:44672
	ds_read_b64_tr_b16 v[52:53], v59 offset:43520
	ds_read_b64_tr_b16 v[54:55], v59 offset:44608
	s_waitcnt lgkmcnt(6)
	v_mfma_f32_16x16x32_bf16 v[20:23], v[36:39], v[24:27], v[20:23]
	v_mfma_f32_16x16x32_bf16 v[28:31], v[40:43], v[24:27], v[28:31]
	s_waitcnt lgkmcnt(2)
	v_mfma_f32_16x16x32_bf16 v[32:35], v[48:51], v[24:27], v[32:35]
	s_waitcnt lgkmcnt(0)
	v_mfma_f32_16x16x32_bf16 v[8:11], v[52:55], v[24:27], v[8:11]
	v_lshl_add_u64 v[24:25], s[0:1], 0, v[144:145]
	v_lshlrev_b32_e32 v144, 9, v56
	v_lshl_add_u64 v[24:25], v[24:25], 0, v[144:145]
	v_add_co_u32_e32 v26, vcc, 0x2000, v24
	v_mfma_f32_16x16x32_bf16 v[0:3], v[36:39], v[44:47], v[0:3]
	s_nop 0
	v_addc_co_u32_e32 v27, vcc, 0, v25, vcc
	s_mov_b64 s[0:1], 0
	v_mfma_f32_16x16x32_bf16 v[4:7], v[40:43], v[44:47], v[4:7]
	v_mfma_f32_16x16x32_bf16 v[16:19], v[48:51], v[44:47], v[16:19]
	v_mfma_f32_16x16x32_bf16 v[12:15], v[52:55], v[44:47], v[12:15]
	global_store_dwordx4 v[24:25], v[20:23], off sc1
	global_store_dwordx4 v[24:25], v[28:31], off offset:64 sc1
	global_store_dwordx4 v[24:25], v[32:35], off offset:128 sc1
	global_store_dwordx4 v[24:25], v[8:11], off offset:192 sc1
	global_store_dwordx4 v[26:27], v[0:3], off sc1
	s_nop 0
	global_store_dwordx4 v[26:27], v[4:7], off offset:64 sc1
	global_store_dwordx4 v[26:27], v[16:19], off offset:128 sc1
	global_store_dwordx4 v[26:27], v[12:15], off offset:192 sc1
	s_barrier
